# P4 epilogue rewritten by hand (same per-element arithmetic, same lane-pair swap and full-line nt stores): packed f32 multiplies for scale and square, SGPR-base + 32-bit offset store addressing, rstd r
# speedup vs baseline: 1.0001x; 1.0001x over previous
.LBB0_754:
	s_lshl_b32 s23, s30, 8
	s_and_b32 s25, s23, 0xc00
	v_add_u32_e32 v155, s25, v149
	ds_read_b32 v160, v155
	ds_read_b32 v162, v155 offset:64
	ds_read_b32 v164, v155 offset:128
	ds_read_b32 v166, v155 offset:192
	ds_read_b32 v170, v155 offset:512
	ds_read_b32 v172, v155 offset:576
	ds_read_b32 v174, v155 offset:640
	ds_read_b32 v176, v155 offset:704
	v_add_u32_e32 v146, s23, v150
	v_lshl_or_b32 v158, s49, 8, v151
	v_lshlrev_b32_e32 v168, 13, v146
	v_add_u32_e32 v168, v168, v136
	v_lshl_add_u32 v168, v158, 1, v168
	s_mov_b32 s98, s60
	s_mov_b32 s99, s61
	s_waitcnt lgkmcnt(7)
	v_pk_mul_f32 v[112:113], v[112:113], v[160:161] op_sel_hi:[1,0]
	v_pk_mul_f32 v[114:115], v[114:115], v[160:161] op_sel_hi:[1,0]
	v_pk_mul_f32 v[116:117], v[116:117], v[160:161] op_sel_hi:[1,0]
	v_pk_mul_f32 v[118:119], v[118:119], v[160:161] op_sel_hi:[1,0]
	v_pk_mul_f32 v[120:121], v[120:121], v[160:161] op_sel_hi:[1,0]
	v_pk_mul_f32 v[122:123], v[122:123], v[160:161] op_sel_hi:[1,0]
	v_pk_mul_f32 v[124:125], v[124:125], v[160:161] op_sel_hi:[1,0]
	v_pk_mul_f32 v[126:127], v[126:127], v[160:161] op_sel_hi:[1,0]
	v_max_f32_e32 v112, 0, v112
	v_max_f32_e32 v113, 0, v113
	v_max_f32_e32 v114, 0, v114
	v_max_f32_e32 v115, 0, v115
	v_max_f32_e32 v116, 0, v116
	v_max_f32_e32 v117, 0, v117
	v_max_f32_e32 v118, 0, v118
	v_max_f32_e32 v119, 0, v119
	v_max_f32_e32 v120, 0, v120
	v_max_f32_e32 v121, 0, v121
	v_max_f32_e32 v122, 0, v122
	v_max_f32_e32 v123, 0, v123
	v_max_f32_e32 v124, 0, v124
	v_max_f32_e32 v125, 0, v125
	v_max_f32_e32 v126, 0, v126
	v_max_f32_e32 v127, 0, v127
	v_pk_mul_f32 v[112:113], v[112:113], v[112:113]
	v_pk_mul_f32 v[114:115], v[114:115], v[114:115]
	v_pk_mul_f32 v[116:117], v[116:117], v[116:117]
	v_pk_mul_f32 v[118:119], v[118:119], v[118:119]
	v_pk_mul_f32 v[120:121], v[120:121], v[120:121]
	v_pk_mul_f32 v[122:123], v[122:123], v[122:123]
	v_pk_mul_f32 v[124:125], v[124:125], v[124:125]
	v_pk_mul_f32 v[126:127], v[126:127], v[126:127]
	v_cvt_pk_bf16_f32 v124, v124, v125
	v_cvt_pk_bf16_f32 v125, v126, v127
	v_cvt_pk_bf16_f32 v126, v120, v121
	v_cvt_pk_bf16_f32 v127, v122, v123
	v_cvt_pk_bf16_f32 v116, v116, v117
	v_cvt_pk_bf16_f32 v117, v118, v119
	v_cvt_pk_bf16_f32 v118, v112, v113
	v_cvt_pk_bf16_f32 v119, v114, v115
	v_cndmask_b32_e64 v178, v124, v116, s[0:1]
	v_cndmask_b32_e64 v179, v125, v117, s[0:1]
	v_cndmask_b32_e64 v180, v126, v118, s[0:1]
	v_cndmask_b32_e64 v181, v127, v119, s[0:1]
	s_add_u32 s100, s98, 0x2000
	s_addc_u32 s101, s99, 0
	v_mov_b32_dpp v182, v178 quad_perm:[1,0,3,2] row_mask:0xf bank_mask:0xf bound_ctrl:1
	v_mov_b32_dpp v183, v179 quad_perm:[1,0,3,2] row_mask:0xf bank_mask:0xf bound_ctrl:1
	v_mov_b32_dpp v184, v180 quad_perm:[1,0,3,2] row_mask:0xf bank_mask:0xf bound_ctrl:1
	v_mov_b32_dpp v185, v181 quad_perm:[1,0,3,2] row_mask:0xf bank_mask:0xf bound_ctrl:1
	v_cndmask_b32_e64 v124, v182, v124, s[0:1]
	v_cndmask_b32_e64 v125, v183, v125, s[0:1]
	v_cndmask_b32_e64 v126, v184, v126, s[0:1]
	v_cndmask_b32_e64 v127, v185, v127, s[0:1]
	v_cndmask_b32_e64 v116, v116, v182, s[0:1]
	v_cndmask_b32_e64 v117, v117, v183, s[0:1]
	v_cndmask_b32_e64 v118, v118, v184, s[0:1]
	v_cndmask_b32_e64 v119, v119, v185, s[0:1]
	global_store_dwordx4 v168, v[124:127], s[98:99] nt
	global_store_dwordx4 v168, v[116:119], s[100:101] nt
	s_add_u32 s98, s60, 0x20000
	s_addc_u32 s99, s61, 0
	s_waitcnt lgkmcnt(6)
	v_pk_mul_f32 v[96:97], v[96:97], v[162:163] op_sel_hi:[1,0]
	v_pk_mul_f32 v[98:99], v[98:99], v[162:163] op_sel_hi:[1,0]
	v_pk_mul_f32 v[100:101], v[100:101], v[162:163] op_sel_hi:[1,0]
	v_pk_mul_f32 v[102:103], v[102:103], v[162:163] op_sel_hi:[1,0]
	v_pk_mul_f32 v[104:105], v[104:105], v[162:163] op_sel_hi:[1,0]
	v_pk_mul_f32 v[106:107], v[106:107], v[162:163] op_sel_hi:[1,0]
	v_pk_mul_f32 v[108:109], v[108:109], v[162:163] op_sel_hi:[1,0]
	v_pk_mul_f32 v[110:111], v[110:111], v[162:163] op_sel_hi:[1,0]
	v_max_f32_e32 v96, 0, v96
	v_max_f32_e32 v97, 0, v97
	v_max_f32_e32 v98, 0, v98
	v_max_f32_e32 v99, 0, v99
	v_max_f32_e32 v100, 0, v100
	v_max_f32_e32 v101, 0, v101
	v_max_f32_e32 v102, 0, v102
	v_max_f32_e32 v103, 0, v103
	v_max_f32_e32 v104, 0, v104
	v_max_f32_e32 v105, 0, v105
	v_max_f32_e32 v106, 0, v106
	v_max_f32_e32 v107, 0, v107
	v_max_f32_e32 v108, 0, v108
	v_max_f32_e32 v109, 0, v109
	v_max_f32_e32 v110, 0, v110
	v_max_f32_e32 v111, 0, v111
	v_pk_mul_f32 v[96:97], v[96:97], v[96:97]
	v_pk_mul_f32 v[98:99], v[98:99], v[98:99]
	v_pk_mul_f32 v[100:101], v[100:101], v[100:101]
	v_pk_mul_f32 v[102:103], v[102:103], v[102:103]
	v_pk_mul_f32 v[104:105], v[104:105], v[104:105]
	v_pk_mul_f32 v[106:107], v[106:107], v[106:107]
	v_pk_mul_f32 v[108:109], v[108:109], v[108:109]
	v_pk_mul_f32 v[110:111], v[110:111], v[110:111]
	v_cvt_pk_bf16_f32 v108, v108, v109
	v_cvt_pk_bf16_f32 v109, v110, v111
	v_cvt_pk_bf16_f32 v110, v104, v105
	v_cvt_pk_bf16_f32 v111, v106, v107
	v_cvt_pk_bf16_f32 v100, v100, v101
	v_cvt_pk_bf16_f32 v101, v102, v103
	v_cvt_pk_bf16_f32 v102, v96, v97
	v_cvt_pk_bf16_f32 v103, v98, v99
	v_cndmask_b32_e64 v178, v108, v100, s[0:1]
	v_cndmask_b32_e64 v179, v109, v101, s[0:1]
	v_cndmask_b32_e64 v180, v110, v102, s[0:1]
	v_cndmask_b32_e64 v181, v111, v103, s[0:1]
	s_add_u32 s100, s98, 0x2000
	s_addc_u32 s101, s99, 0
	v_mov_b32_dpp v182, v178 quad_perm:[1,0,3,2] row_mask:0xf bank_mask:0xf bound_ctrl:1
	v_mov_b32_dpp v183, v179 quad_perm:[1,0,3,2] row_mask:0xf bank_mask:0xf bound_ctrl:1
	v_mov_b32_dpp v184, v180 quad_perm:[1,0,3,2] row_mask:0xf bank_mask:0xf bound_ctrl:1
	v_mov_b32_dpp v185, v181 quad_perm:[1,0,3,2] row_mask:0xf bank_mask:0xf bound_ctrl:1
	v_cndmask_b32_e64 v108, v182, v108, s[0:1]
	v_cndmask_b32_e64 v109, v183, v109, s[0:1]
	v_cndmask_b32_e64 v110, v184, v110, s[0:1]
	v_cndmask_b32_e64 v111, v185, v111, s[0:1]
	v_cndmask_b32_e64 v100, v100, v182, s[0:1]
	v_cndmask_b32_e64 v101, v101, v183, s[0:1]
	v_cndmask_b32_e64 v102, v102, v184, s[0:1]
	v_cndmask_b32_e64 v103, v103, v185, s[0:1]
	global_store_dwordx4 v168, v[108:111], s[98:99] nt
	global_store_dwordx4 v168, v[100:103], s[100:101] nt
	s_add_u32 s98, s60, 0x40000
	s_addc_u32 s99, s61, 0
	s_waitcnt lgkmcnt(5)
	v_pk_mul_f32 v[80:81], v[80:81], v[164:165] op_sel_hi:[1,0]
	v_pk_mul_f32 v[82:83], v[82:83], v[164:165] op_sel_hi:[1,0]
	v_pk_mul_f32 v[84:85], v[84:85], v[164:165] op_sel_hi:[1,0]
	v_pk_mul_f32 v[86:87], v[86:87], v[164:165] op_sel_hi:[1,0]
	v_pk_mul_f32 v[88:89], v[88:89], v[164:165] op_sel_hi:[1,0]
	v_pk_mul_f32 v[90:91], v[90:91], v[164:165] op_sel_hi:[1,0]
	v_pk_mul_f32 v[92:93], v[92:93], v[164:165] op_sel_hi:[1,0]
	v_pk_mul_f32 v[94:95], v[94:95], v[164:165] op_sel_hi:[1,0]
	v_max_f32_e32 v80, 0, v80
	v_max_f32_e32 v81, 0, v81
	v_max_f32_e32 v82, 0, v82
	v_max_f32_e32 v83, 0, v83
	v_max_f32_e32 v84, 0, v84
	v_max_f32_e32 v85, 0, v85
	v_max_f32_e32 v86, 0, v86
	v_max_f32_e32 v87, 0, v87
	v_max_f32_e32 v88, 0, v88
	v_max_f32_e32 v89, 0, v89
	v_max_f32_e32 v90, 0, v90
	v_max_f32_e32 v91, 0, v91
	v_max_f32_e32 v92, 0, v92
	v_max_f32_e32 v93, 0, v93
	v_max_f32_e32 v94, 0, v94
	v_max_f32_e32 v95, 0, v95
	v_pk_mul_f32 v[80:81], v[80:81], v[80:81]
	v_pk_mul_f32 v[82:83], v[82:83], v[82:83]
	v_pk_mul_f32 v[84:85], v[84:85], v[84:85]
	v_pk_mul_f32 v[86:87], v[86:87], v[86:87]
	v_pk_mul_f32 v[88:89], v[88:89], v[88:89]
	v_pk_mul_f32 v[90:91], v[90:91], v[90:91]
	v_pk_mul_f32 v[92:93], v[92:93], v[92:93]
	v_pk_mul_f32 v[94:95], v[94:95], v[94:95]
	v_cvt_pk_bf16_f32 v92, v92, v93
	v_cvt_pk_bf16_f32 v93, v94, v95
	v_cvt_pk_bf16_f32 v94, v88, v89
	v_cvt_pk_bf16_f32 v95, v90, v91
	v_cvt_pk_bf16_f32 v84, v84, v85
	v_cvt_pk_bf16_f32 v85, v86, v87
	v_cvt_pk_bf16_f32 v86, v80, v81
	v_cvt_pk_bf16_f32 v87, v82, v83
	v_cndmask_b32_e64 v178, v92, v84, s[0:1]
	v_cndmask_b32_e64 v179, v93, v85, s[0:1]
	v_cndmask_b32_e64 v180, v94, v86, s[0:1]
	v_cndmask_b32_e64 v181, v95, v87, s[0:1]
	s_add_u32 s100, s98, 0x2000
	s_addc_u32 s101, s99, 0
	v_mov_b32_dpp v182, v178 quad_perm:[1,0,3,2] row_mask:0xf bank_mask:0xf bound_ctrl:1
	v_mov_b32_dpp v183, v179 quad_perm:[1,0,3,2] row_mask:0xf bank_mask:0xf bound_ctrl:1
	v_mov_b32_dpp v184, v180 quad_perm:[1,0,3,2] row_mask:0xf bank_mask:0xf bound_ctrl:1
	v_mov_b32_dpp v185, v181 quad_perm:[1,0,3,2] row_mask:0xf bank_mask:0xf bound_ctrl:1
	v_cndmask_b32_e64 v92, v182, v92, s[0:1]
	v_cndmask_b32_e64 v93, v183, v93, s[0:1]
	v_cndmask_b32_e64 v94, v184, v94, s[0:1]
	v_cndmask_b32_e64 v95, v185, v95, s[0:1]
	v_cndmask_b32_e64 v84, v84, v182, s[0:1]
	v_cndmask_b32_e64 v85, v85, v183, s[0:1]
	v_cndmask_b32_e64 v86, v86, v184, s[0:1]
	v_cndmask_b32_e64 v87, v87, v185, s[0:1]
	global_store_dwordx4 v168, v[92:95], s[98:99] nt
	global_store_dwordx4 v168, v[84:87], s[100:101] nt
	s_add_u32 s98, s60, 0x60000
	s_addc_u32 s99, s61, 0
	s_waitcnt lgkmcnt(4)
	v_pk_mul_f32 v[64:65], v[64:65], v[166:167] op_sel_hi:[1,0]
	v_pk_mul_f32 v[66:67], v[66:67], v[166:167] op_sel_hi:[1,0]
	v_pk_mul_f32 v[68:69], v[68:69], v[166:167] op_sel_hi:[1,0]
	v_pk_mul_f32 v[70:71], v[70:71], v[166:167] op_sel_hi:[1,0]
	v_pk_mul_f32 v[72:73], v[72:73], v[166:167] op_sel_hi:[1,0]
	v_pk_mul_f32 v[74:75], v[74:75], v[166:167] op_sel_hi:[1,0]
	v_pk_mul_f32 v[76:77], v[76:77], v[166:167] op_sel_hi:[1,0]
	v_pk_mul_f32 v[78:79], v[78:79], v[166:167] op_sel_hi:[1,0]
	v_max_f32_e32 v64, 0, v64
	v_max_f32_e32 v65, 0, v65
	v_max_f32_e32 v66, 0, v66
	v_max_f32_e32 v67, 0, v67
	v_max_f32_e32 v68, 0, v68
	v_max_f32_e32 v69, 0, v69
	v_max_f32_e32 v70, 0, v70
	v_max_f32_e32 v71, 0, v71
	v_max_f32_e32 v72, 0, v72
	v_max_f32_e32 v73, 0, v73
	v_max_f32_e32 v74, 0, v74
	v_max_f32_e32 v75, 0, v75
	v_max_f32_e32 v76, 0, v76
	v_max_f32_e32 v77, 0, v77
	v_max_f32_e32 v78, 0, v78
	v_max_f32_e32 v79, 0, v79
	v_pk_mul_f32 v[64:65], v[64:65], v[64:65]
	v_pk_mul_f32 v[66:67], v[66:67], v[66:67]
	v_pk_mul_f32 v[68:69], v[68:69], v[68:69]
	v_pk_mul_f32 v[70:71], v[70:71], v[70:71]
	v_pk_mul_f32 v[72:73], v[72:73], v[72:73]
	v_pk_mul_f32 v[74:75], v[74:75], v[74:75]
	v_pk_mul_f32 v[76:77], v[76:77], v[76:77]
	v_pk_mul_f32 v[78:79], v[78:79], v[78:79]
	v_cvt_pk_bf16_f32 v76, v76, v77
	v_cvt_pk_bf16_f32 v77, v78, v79
	v_cvt_pk_bf16_f32 v78, v72, v73
	v_cvt_pk_bf16_f32 v79, v74, v75
	v_cvt_pk_bf16_f32 v68, v68, v69
	v_cvt_pk_bf16_f32 v69, v70, v71
	v_cvt_pk_bf16_f32 v70, v64, v65
	v_cvt_pk_bf16_f32 v71, v66, v67
	v_cndmask_b32_e64 v178, v76, v68, s[0:1]
	v_cndmask_b32_e64 v179, v77, v69, s[0:1]
	v_cndmask_b32_e64 v180, v78, v70, s[0:1]
	v_cndmask_b32_e64 v181, v79, v71, s[0:1]
	s_add_u32 s100, s98, 0x2000
	s_addc_u32 s101, s99, 0
	v_mov_b32_dpp v182, v178 quad_perm:[1,0,3,2] row_mask:0xf bank_mask:0xf bound_ctrl:1
	v_mov_b32_dpp v183, v179 quad_perm:[1,0,3,2] row_mask:0xf bank_mask:0xf bound_ctrl:1
	v_mov_b32_dpp v184, v180 quad_perm:[1,0,3,2] row_mask:0xf bank_mask:0xf bound_ctrl:1
	v_mov_b32_dpp v185, v181 quad_perm:[1,0,3,2] row_mask:0xf bank_mask:0xf bound_ctrl:1
	v_cndmask_b32_e64 v76, v182, v76, s[0:1]
	v_cndmask_b32_e64 v77, v183, v77, s[0:1]
	v_cndmask_b32_e64 v78, v184, v78, s[0:1]
	v_cndmask_b32_e64 v79, v185, v79, s[0:1]
	v_cndmask_b32_e64 v68, v68, v182, s[0:1]
	v_cndmask_b32_e64 v69, v69, v183, s[0:1]
	v_cndmask_b32_e64 v70, v70, v184, s[0:1]
	v_cndmask_b32_e64 v71, v71, v185, s[0:1]
	global_store_dwordx4 v168, v[76:79], s[98:99] nt
	global_store_dwordx4 v168, v[68:71], s[100:101] nt
	s_add_u32 s98, s60, 0x100000
	s_addc_u32 s99, s61, 0
	s_waitcnt lgkmcnt(3)
	v_pk_mul_f32 v[48:49], v[48:49], v[170:171] op_sel_hi:[1,0]
	v_pk_mul_f32 v[50:51], v[50:51], v[170:171] op_sel_hi:[1,0]
	v_pk_mul_f32 v[52:53], v[52:53], v[170:171] op_sel_hi:[1,0]
	v_pk_mul_f32 v[54:55], v[54:55], v[170:171] op_sel_hi:[1,0]
	v_pk_mul_f32 v[56:57], v[56:57], v[170:171] op_sel_hi:[1,0]
	v_pk_mul_f32 v[58:59], v[58:59], v[170:171] op_sel_hi:[1,0]
	v_pk_mul_f32 v[60:61], v[60:61], v[170:171] op_sel_hi:[1,0]
	v_pk_mul_f32 v[62:63], v[62:63], v[170:171] op_sel_hi:[1,0]
	v_max_f32_e32 v48, 0, v48
	v_max_f32_e32 v49, 0, v49
	v_max_f32_e32 v50, 0, v50
	v_max_f32_e32 v51, 0, v51
	v_max_f32_e32 v52, 0, v52
	v_max_f32_e32 v53, 0, v53
	v_max_f32_e32 v54, 0, v54
	v_max_f32_e32 v55, 0, v55
	v_max_f32_e32 v56, 0, v56
	v_max_f32_e32 v57, 0, v57
	v_max_f32_e32 v58, 0, v58
	v_max_f32_e32 v59, 0, v59
	v_max_f32_e32 v60, 0, v60
	v_max_f32_e32 v61, 0, v61
	v_max_f32_e32 v62, 0, v62
	v_max_f32_e32 v63, 0, v63
	v_pk_mul_f32 v[48:49], v[48:49], v[48:49]
	v_pk_mul_f32 v[50:51], v[50:51], v[50:51]
	v_pk_mul_f32 v[52:53], v[52:53], v[52:53]
	v_pk_mul_f32 v[54:55], v[54:55], v[54:55]
	v_pk_mul_f32 v[56:57], v[56:57], v[56:57]
	v_pk_mul_f32 v[58:59], v[58:59], v[58:59]
	v_pk_mul_f32 v[60:61], v[60:61], v[60:61]
	v_pk_mul_f32 v[62:63], v[62:63], v[62:63]
	v_cvt_pk_bf16_f32 v60, v60, v61
	v_cvt_pk_bf16_f32 v61, v62, v63
	v_cvt_pk_bf16_f32 v62, v56, v57
	v_cvt_pk_bf16_f32 v63, v58, v59
	v_cvt_pk_bf16_f32 v52, v52, v53
	v_cvt_pk_bf16_f32 v53, v54, v55
	v_cvt_pk_bf16_f32 v54, v48, v49
	v_cvt_pk_bf16_f32 v55, v50, v51
	v_cndmask_b32_e64 v178, v60, v52, s[0:1]
	v_cndmask_b32_e64 v179, v61, v53, s[0:1]
	v_cndmask_b32_e64 v180, v62, v54, s[0:1]
	v_cndmask_b32_e64 v181, v63, v55, s[0:1]
	s_add_u32 s100, s98, 0x2000
	s_addc_u32 s101, s99, 0
	v_mov_b32_dpp v182, v178 quad_perm:[1,0,3,2] row_mask:0xf bank_mask:0xf bound_ctrl:1
	v_mov_b32_dpp v183, v179 quad_perm:[1,0,3,2] row_mask:0xf bank_mask:0xf bound_ctrl:1
	v_mov_b32_dpp v184, v180 quad_perm:[1,0,3,2] row_mask:0xf bank_mask:0xf bound_ctrl:1
	v_mov_b32_dpp v185, v181 quad_perm:[1,0,3,2] row_mask:0xf bank_mask:0xf bound_ctrl:1
	v_cndmask_b32_e64 v60, v182, v60, s[0:1]
	v_cndmask_b32_e64 v61, v183, v61, s[0:1]
	v_cndmask_b32_e64 v62, v184, v62, s[0:1]
	v_cndmask_b32_e64 v63, v185, v63, s[0:1]
	v_cndmask_b32_e64 v52, v52, v182, s[0:1]
	v_cndmask_b32_e64 v53, v53, v183, s[0:1]
	v_cndmask_b32_e64 v54, v54, v184, s[0:1]
	v_cndmask_b32_e64 v55, v55, v185, s[0:1]
	global_store_dwordx4 v168, v[60:63], s[98:99] nt
	global_store_dwordx4 v168, v[52:55], s[100:101] nt
	s_add_u32 s98, s60, 0x120000
	s_addc_u32 s99, s61, 0
	s_waitcnt lgkmcnt(2)
	v_pk_mul_f32 v[32:33], v[32:33], v[172:173] op_sel_hi:[1,0]
	v_pk_mul_f32 v[34:35], v[34:35], v[172:173] op_sel_hi:[1,0]
	v_pk_mul_f32 v[36:37], v[36:37], v[172:173] op_sel_hi:[1,0]
	v_pk_mul_f32 v[38:39], v[38:39], v[172:173] op_sel_hi:[1,0]
	v_pk_mul_f32 v[40:41], v[40:41], v[172:173] op_sel_hi:[1,0]
	v_pk_mul_f32 v[42:43], v[42:43], v[172:173] op_sel_hi:[1,0]
	v_pk_mul_f32 v[44:45], v[44:45], v[172:173] op_sel_hi:[1,0]
	v_pk_mul_f32 v[46:47], v[46:47], v[172:173] op_sel_hi:[1,0]
	v_max_f32_e32 v32, 0, v32
	v_max_f32_e32 v33, 0, v33
	v_max_f32_e32 v34, 0, v34
	v_max_f32_e32 v35, 0, v35
	v_max_f32_e32 v36, 0, v36
	v_max_f32_e32 v37, 0, v37
	v_max_f32_e32 v38, 0, v38
	v_max_f32_e32 v39, 0, v39
	v_max_f32_e32 v40, 0, v40
	v_max_f32_e32 v41, 0, v41
	v_max_f32_e32 v42, 0, v42
	v_max_f32_e32 v43, 0, v43
	v_max_f32_e32 v44, 0, v44
	v_max_f32_e32 v45, 0, v45
	v_max_f32_e32 v46, 0, v46
	v_max_f32_e32 v47, 0, v47
	v_pk_mul_f32 v[32:33], v[32:33], v[32:33]
	v_pk_mul_f32 v[34:35], v[34:35], v[34:35]
	v_pk_mul_f32 v[36:37], v[36:37], v[36:37]
	v_pk_mul_f32 v[38:39], v[38:39], v[38:39]
	v_pk_mul_f32 v[40:41], v[40:41], v[40:41]
	v_pk_mul_f32 v[42:43], v[42:43], v[42:43]
	v_pk_mul_f32 v[44:45], v[44:45], v[44:45]
	v_pk_mul_f32 v[46:47], v[46:47], v[46:47]
	v_cvt_pk_bf16_f32 v44, v44, v45
	v_cvt_pk_bf16_f32 v45, v46, v47
	v_cvt_pk_bf16_f32 v46, v40, v41
	v_cvt_pk_bf16_f32 v47, v42, v43
	v_cvt_pk_bf16_f32 v36, v36, v37
	v_cvt_pk_bf16_f32 v37, v38, v39
	v_cvt_pk_bf16_f32 v38, v32, v33
	v_cvt_pk_bf16_f32 v39, v34, v35
	v_cndmask_b32_e64 v178, v44, v36, s[0:1]
	v_cndmask_b32_e64 v179, v45, v37, s[0:1]
	v_cndmask_b32_e64 v180, v46, v38, s[0:1]
	v_cndmask_b32_e64 v181, v47, v39, s[0:1]
	s_add_u32 s100, s98, 0x2000
	s_addc_u32 s101, s99, 0
	v_mov_b32_dpp v182, v178 quad_perm:[1,0,3,2] row_mask:0xf bank_mask:0xf bound_ctrl:1
	v_mov_b32_dpp v183, v179 quad_perm:[1,0,3,2] row_mask:0xf bank_mask:0xf bound_ctrl:1
	v_mov_b32_dpp v184, v180 quad_perm:[1,0,3,2] row_mask:0xf bank_mask:0xf bound_ctrl:1
	v_mov_b32_dpp v185, v181 quad_perm:[1,0,3,2] row_mask:0xf bank_mask:0xf bound_ctrl:1
	v_cndmask_b32_e64 v44, v182, v44, s[0:1]
	v_cndmask_b32_e64 v45, v183, v45, s[0:1]
	v_cndmask_b32_e64 v46, v184, v46, s[0:1]
	v_cndmask_b32_e64 v47, v185, v47, s[0:1]
	v_cndmask_b32_e64 v36, v36, v182, s[0:1]
	v_cndmask_b32_e64 v37, v37, v183, s[0:1]
	v_cndmask_b32_e64 v38, v38, v184, s[0:1]
	v_cndmask_b32_e64 v39, v39, v185, s[0:1]
	global_store_dwordx4 v168, v[44:47], s[98:99] nt
	global_store_dwordx4 v168, v[36:39], s[100:101] nt
	s_add_u32 s98, s60, 0x140000
	s_addc_u32 s99, s61, 0
	s_waitcnt lgkmcnt(1)
	v_pk_mul_f32 v[16:17], v[16:17], v[174:175] op_sel_hi:[1,0]
	v_pk_mul_f32 v[18:19], v[18:19], v[174:175] op_sel_hi:[1,0]
	v_pk_mul_f32 v[20:21], v[20:21], v[174:175] op_sel_hi:[1,0]
	v_pk_mul_f32 v[22:23], v[22:23], v[174:175] op_sel_hi:[1,0]
	v_pk_mul_f32 v[24:25], v[24:25], v[174:175] op_sel_hi:[1,0]
	v_pk_mul_f32 v[26:27], v[26:27], v[174:175] op_sel_hi:[1,0]
	v_pk_mul_f32 v[28:29], v[28:29], v[174:175] op_sel_hi:[1,0]
	v_pk_mul_f32 v[30:31], v[30:31], v[174:175] op_sel_hi:[1,0]
	v_max_f32_e32 v16, 0, v16
	v_max_f32_e32 v17, 0, v17
	v_max_f32_e32 v18, 0, v18
	v_max_f32_e32 v19, 0, v19
	v_max_f32_e32 v20, 0, v20
	v_max_f32_e32 v21, 0, v21
	v_max_f32_e32 v22, 0, v22
	v_max_f32_e32 v23, 0, v23
	v_max_f32_e32 v24, 0, v24
	v_max_f32_e32 v25, 0, v25
	v_max_f32_e32 v26, 0, v26
	v_max_f32_e32 v27, 0, v27
	v_max_f32_e32 v28, 0, v28
	v_max_f32_e32 v29, 0, v29
	v_max_f32_e32 v30, 0, v30
	v_max_f32_e32 v31, 0, v31
	v_pk_mul_f32 v[16:17], v[16:17], v[16:17]
	v_pk_mul_f32 v[18:19], v[18:19], v[18:19]
	v_pk_mul_f32 v[20:21], v[20:21], v[20:21]
	v_pk_mul_f32 v[22:23], v[22:23], v[22:23]
	v_pk_mul_f32 v[24:25], v[24:25], v[24:25]
	v_pk_mul_f32 v[26:27], v[26:27], v[26:27]
	v_pk_mul_f32 v[28:29], v[28:29], v[28:29]
	v_pk_mul_f32 v[30:31], v[30:31], v[30:31]
	v_cvt_pk_bf16_f32 v28, v28, v29
	v_cvt_pk_bf16_f32 v29, v30, v31
	v_cvt_pk_bf16_f32 v30, v24, v25
	v_cvt_pk_bf16_f32 v31, v26, v27
	v_cvt_pk_bf16_f32 v20, v20, v21
	v_cvt_pk_bf16_f32 v21, v22, v23
	v_cvt_pk_bf16_f32 v22, v16, v17
	v_cvt_pk_bf16_f32 v23, v18, v19
	v_cndmask_b32_e64 v178, v28, v20, s[0:1]
	v_cndmask_b32_e64 v179, v29, v21, s[0:1]
	v_cndmask_b32_e64 v180, v30, v22, s[0:1]
	v_cndmask_b32_e64 v181, v31, v23, s[0:1]
	s_add_u32 s100, s98, 0x2000
	s_addc_u32 s101, s99, 0
	v_mov_b32_dpp v182, v178 quad_perm:[1,0,3,2] row_mask:0xf bank_mask:0xf bound_ctrl:1
	v_mov_b32_dpp v183, v179 quad_perm:[1,0,3,2] row_mask:0xf bank_mask:0xf bound_ctrl:1
	v_mov_b32_dpp v184, v180 quad_perm:[1,0,3,2] row_mask:0xf bank_mask:0xf bound_ctrl:1
	v_mov_b32_dpp v185, v181 quad_perm:[1,0,3,2] row_mask:0xf bank_mask:0xf bound_ctrl:1
	v_cndmask_b32_e64 v28, v182, v28, s[0:1]
	v_cndmask_b32_e64 v29, v183, v29, s[0:1]
	v_cndmask_b32_e64 v30, v184, v30, s[0:1]
	v_cndmask_b32_e64 v31, v185, v31, s[0:1]
	v_cndmask_b32_e64 v20, v20, v182, s[0:1]
	v_cndmask_b32_e64 v21, v21, v183, s[0:1]
	v_cndmask_b32_e64 v22, v22, v184, s[0:1]
	v_cndmask_b32_e64 v23, v23, v185, s[0:1]
	global_store_dwordx4 v168, v[28:31], s[98:99] nt
	global_store_dwordx4 v168, v[20:23], s[100:101] nt
	s_add_u32 s98, s60, 0x160000
	s_addc_u32 s99, s61, 0
	s_waitcnt lgkmcnt(0)
	v_pk_mul_f32 v[0:1], v[0:1], v[176:177] op_sel_hi:[1,0]
	v_pk_mul_f32 v[2:3], v[2:3], v[176:177] op_sel_hi:[1,0]
	v_pk_mul_f32 v[4:5], v[4:5], v[176:177] op_sel_hi:[1,0]
	v_pk_mul_f32 v[6:7], v[6:7], v[176:177] op_sel_hi:[1,0]
	v_pk_mul_f32 v[8:9], v[8:9], v[176:177] op_sel_hi:[1,0]
	v_pk_mul_f32 v[10:11], v[10:11], v[176:177] op_sel_hi:[1,0]
	v_pk_mul_f32 v[12:13], v[12:13], v[176:177] op_sel_hi:[1,0]
	v_pk_mul_f32 v[14:15], v[14:15], v[176:177] op_sel_hi:[1,0]
	v_max_f32_e32 v0, 0, v0
	v_max_f32_e32 v1, 0, v1
	v_max_f32_e32 v2, 0, v2
	v_max_f32_e32 v3, 0, v3
	v_max_f32_e32 v4, 0, v4
	v_max_f32_e32 v5, 0, v5
	v_max_f32_e32 v6, 0, v6
	v_max_f32_e32 v7, 0, v7
	v_max_f32_e32 v8, 0, v8
	v_max_f32_e32 v9, 0, v9
	v_max_f32_e32 v10, 0, v10
	v_max_f32_e32 v11, 0, v11
	v_max_f32_e32 v12, 0, v12
	v_max_f32_e32 v13, 0, v13
	v_max_f32_e32 v14, 0, v14
	v_max_f32_e32 v15, 0, v15
	v_pk_mul_f32 v[0:1], v[0:1], v[0:1]
	v_pk_mul_f32 v[2:3], v[2:3], v[2:3]
	v_pk_mul_f32 v[4:5], v[4:5], v[4:5]
	v_pk_mul_f32 v[6:7], v[6:7], v[6:7]
	v_pk_mul_f32 v[8:9], v[8:9], v[8:9]
	v_pk_mul_f32 v[10:11], v[10:11], v[10:11]
	v_pk_mul_f32 v[12:13], v[12:13], v[12:13]
	v_pk_mul_f32 v[14:15], v[14:15], v[14:15]
	v_cvt_pk_bf16_f32 v12, v12, v13
	v_cvt_pk_bf16_f32 v13, v14, v15
	v_cvt_pk_bf16_f32 v14, v8, v9
	v_cvt_pk_bf16_f32 v15, v10, v11
	v_cvt_pk_bf16_f32 v4, v4, v5
	v_cvt_pk_bf16_f32 v5, v6, v7
	v_cvt_pk_bf16_f32 v6, v0, v1
	v_cvt_pk_bf16_f32 v7, v2, v3
	v_cndmask_b32_e64 v178, v12, v4, s[0:1]
	v_cndmask_b32_e64 v179, v13, v5, s[0:1]
	v_cndmask_b32_e64 v180, v14, v6, s[0:1]
	v_cndmask_b32_e64 v181, v15, v7, s[0:1]
	s_add_u32 s100, s98, 0x2000
	s_addc_u32 s101, s99, 0
	v_mov_b32_dpp v182, v178 quad_perm:[1,0,3,2] row_mask:0xf bank_mask:0xf bound_ctrl:1
	v_mov_b32_dpp v183, v179 quad_perm:[1,0,3,2] row_mask:0xf bank_mask:0xf bound_ctrl:1
	v_mov_b32_dpp v184, v180 quad_perm:[1,0,3,2] row_mask:0xf bank_mask:0xf bound_ctrl:1
	v_mov_b32_dpp v185, v181 quad_perm:[1,0,3,2] row_mask:0xf bank_mask:0xf bound_ctrl:1
	v_cndmask_b32_e64 v12, v182, v12, s[0:1]
	v_cndmask_b32_e64 v13, v183, v13, s[0:1]
	v_cndmask_b32_e64 v14, v184, v14, s[0:1]
	v_cndmask_b32_e64 v15, v185, v15, s[0:1]
	v_cndmask_b32_e64 v4, v4, v182, s[0:1]
	v_cndmask_b32_e64 v5, v5, v183, s[0:1]
	v_cndmask_b32_e64 v6, v6, v184, s[0:1]
	v_cndmask_b32_e64 v7, v7, v185, s[0:1]
	global_store_dwordx4 v168, v[12:15], s[98:99] nt
	global_store_dwordx4 v168, v[4:7], s[100:101] nt
	s_andn2_b64 vcc, exec, s[6:7]
	s_mov_b64 s[6:7], -1
	s_cbranch_vccnz .LBB0_743
	s_andn2_b64 vcc, exec, s[10:11]
	s_cbranch_vccnz .LBB0_742
	s_barrier
	s_branch .LBB0_742
